# P2 pooling tasks: input-row staging merged into one load batch + one wait (was 3 dependent batches), first mix-weight fragments loaded up front
# speedup vs baseline: 1.0023x; 1.0023x over previous
.LBB0_326:
	s_add_i32 s8, s48, -15
	global_load_dwordx4 v[70:73], v[144:145], off
	global_load_dwordx4 v[74:77], v[146:147], off
	global_load_dwordx4 v[78:81], v[148:149], off
	global_load_dwordx4 v[66:69], v[150:151], off
	v_mov_b32_e32 v2, 0
	s_andn2_b64 vcc, exec, s[10:11]
	v_mov_b32_e32 v44, 0
	v_mov_b32_e32 v45, 0
	v_mov_b32_e32 v46, 0
	v_mov_b32_e32 v47, 0
	s_cbranch_vccnz .LBB0_328
	v_add_u32_e32 v3, s8, v195
	v_mad_i64_i32 v[4:5], s[10:11], v3, s37, v[132:133]
	v_add_u32_e32 v3, s8, v199
	v_mad_i64_i32 v[6:7], s[10:11], v3, s37, v[132:133]
	v_add_u32_e32 v3, s8, v200
	global_load_dwordx4 v[36:39], v[4:5], off offset:768
	global_load_dwordx4 v[40:43], v[6:7], off offset:768
	v_mad_i64_i32 v[4:5], s[10:11], v3, s37, v[132:133]
	global_load_dwordx4 v[44:47], v[4:5], off offset:768
	v_add_u32_e32 v3, v157, v198
	v_mov_b32_e32 v52, v3
.LBB0_328:
	v_add_u32_e32 v53, v157, v201
	s_or_b64 s[10:11], s[0:1], s[6:7]
	v_mov_b32_e32 v3, 0
	v_mov_b32_e32 v4, 0
	v_mov_b32_e32 v5, 0
	s_and_saveexec_b64 s[6:7], s[10:11]
	s_cbranch_execz .LBB0_330
	v_add_u32_e32 v2, s8, v202
	v_mad_i64_i32 v[2:3], s[10:11], v2, s37, v[132:133]
	global_load_dwordx4 v[2:5], v[2:3], off offset:768
.LBB0_330:
	s_or_b64 exec, exec, s[6:7]
	v_add_u32_e32 v6, s8, v204
	v_add_u32_e32 v8, s8, v205
	v_mad_i64_i32 v[6:7], s[6:7], v6, s37, v[132:133]
	v_mad_i64_i32 v[12:13], s[6:7], v8, s37, v[132:133]
	global_load_dwordx4 v[8:11], v[6:7], off offset:768
	s_nop 0
	global_load_dwordx4 v[12:15], v[12:13], off offset:768
	v_add_u32_e32 v6, s8, v206
	v_add_u32_e32 v16, s8, v207
	v_mad_i64_i32 v[6:7], s[6:7], v6, s37, v[132:133]
	v_mad_i64_i32 v[20:21], s[6:7], v16, s37, v[132:133]
	global_load_dwordx4 v[16:19], v[6:7], off offset:768
	s_nop 0
	global_load_dwordx4 v[20:23], v[20:21], off offset:768
	v_add_u32_e32 v6, s8, v208
	v_add_u32_e32 v24, s8, v209
	v_mad_i64_i32 v[6:7], s[6:7], v6, s37, v[132:133]
	v_mad_i64_i32 v[28:29], s[6:7], v24, s37, v[132:133]
	global_load_dwordx4 v[24:27], v[6:7], off offset:768
	s_nop 0
	global_load_dwordx4 v[28:31], v[28:29], off offset:768
	v_add_u32_e32 v6, s8, v210
	v_mad_i64_i32 v[6:7], s[6:7], v6, s37, v[132:133]
	global_load_dwordx4 v[32:35], v[6:7], off offset:768
	s_and_saveexec_b64 s[6:7], s[4:5]
	v_add_u32_e32 v48, s8, v211
	v_mad_i64_i32 v[48:49], s[10:11], v48, s37, v[132:133]
	global_load_dwordx4 v[48:51], v[48:49], off offset:768
	s_or_b64 exec, exec, s[6:7]
	v_add_u32_e32 v6, v157, v203
	s_waitcnt vmcnt(0)
	ds_write_b128 v53, v[44:47]
	s_cmp_eq_u32 s28, 0
	s_cbranch_scc1 .Lpsm_0
	ds_write_b128 v52, v[36:39]
	ds_write_b128 v52, v[40:43] offset:1088
.Lpsm_0:
	ds_write_b128 v6, v[2:5]
	ds_write_b128 v6, v[8:11] offset:1088
	ds_write_b128 v6, v[12:15] offset:2176
	ds_write_b128 v6, v[16:19] offset:3264
	ds_write_b128 v6, v[20:23] offset:4352
	ds_write_b128 v6, v[24:27] offset:5440
	ds_write_b128 v6, v[28:31] offset:6528
	ds_write_b128 v6, v[32:35] offset:7616
	s_and_saveexec_b64 s[6:7], s[4:5]
	s_cbranch_execz .LBB0_332
	ds_write_b128 v6, v[48:51] offset:8704
.LBB0_332:
	s_or_b64 exec, exec, s[6:7]
	s_waitcnt lgkmcnt(0)
	v_or_b32_e32 v2, s28, v1
	v_min_u32_e32 v3, 15, v2
	v_add_u32_e32 v3, 1, v3
	v_cvt_f32_ubyte0_e32 v3, v3
	v_div_scale_f32 v4, s[6:7], v3, v3, 1.0
	v_rcp_f32_e32 v5, v4
	s_ashr_i32 s8, s30, 6
	s_mul_i32 s10, s8, 15
	v_cmp_lt_u32_e64 s[6:7], s41, v2
	v_fma_f32 v6, -v4, v5, 1.0
	v_fmac_f32_e32 v5, v6, v5
	v_div_scale_f32 v6, vcc, 1.0, v3, 1.0
	v_mul_f32_e32 v7, v6, v5
	v_fma_f32 v8, -v4, v7, v6
	v_fmac_f32_e32 v7, v8, v5
	v_fma_f32 v4, -v4, v7, v6
	v_div_fmas_f32 v4, v4, v5, v7
	v_div_fixup_f32 v159, v4, v3, 1.0
	s_ashr_i32 s11, s10, 31
	v_add_u32_e32 v2, 0xfffff80f, v2
	v_mov_b32_e32 v3, v155
	v_lshl_add_u64 v[2:3], v[2:3], 0, s[10:11]
	v_lshlrev_b64 v[2:3], 11, v[2:3]
	v_lshl_add_u64 v[2:3], s[70:71], 0, v[2:3]
	v_mov_b32_e32 v163, v155
	v_lshl_add_u64 v[2:3], v[2:3], 0, v[162:163]
	v_lshl_add_u64 v[192:193], v[2:3], 0, s[16:17]
	v_mov_b32_e32 v2, 0
	s_mov_b32 s49, 0
	s_mov_b64 s[10:11], 0
	v_mov_b32_e32 v3, v2
	v_mov_b32_e32 v4, v2
	v_mov_b32_e32 v5, v2
	v_mov_b32_e32 v6, v2
	v_mov_b32_e32 v7, v2
	v_mov_b32_e32 v8, v2
	v_mov_b32_e32 v9, v2
	v_mov_b32_e32 v10, v2
	v_mov_b32_e32 v11, v2
	v_mov_b32_e32 v12, v2
	v_mov_b32_e32 v13, v2
	v_mov_b32_e32 v14, v2
	v_mov_b32_e32 v15, v2
	v_mov_b32_e32 v16, v2
	v_mov_b32_e32 v17, v2
	v_mov_b32_e32 v18, v2
	v_mov_b32_e32 v19, v2
	v_mov_b32_e32 v20, v2
	v_mov_b32_e32 v21, v2
	v_mov_b32_e32 v22, v2
	v_mov_b32_e32 v23, v2
	v_mov_b32_e32 v24, v2
	v_mov_b32_e32 v25, v2
	v_mov_b32_e32 v26, v2
	v_mov_b32_e32 v27, v2
	v_mov_b32_e32 v28, v2
	v_mov_b32_e32 v29, v2
	v_mov_b32_e32 v30, v2
	v_mov_b32_e32 v31, v2
	v_mov_b32_e32 v32, v2
	v_mov_b32_e32 v33, v2
	v_mov_b32_e32 v34, v2
	v_mov_b32_e32 v35, v2
	v_mov_b32_e32 v36, v2
	v_mov_b32_e32 v37, v2
	v_mov_b32_e32 v38, v2
	v_mov_b32_e32 v39, v2
	v_mov_b32_e32 v40, v2
	v_mov_b32_e32 v41, v2
	v_mov_b32_e32 v42, v2
	v_mov_b32_e32 v43, v2
	v_mov_b32_e32 v44, v2
	v_mov_b32_e32 v45, v2
	v_mov_b32_e32 v46, v2
	v_mov_b32_e32 v47, v2
	s_waitcnt vmcnt(3)
	v_mov_b64_e32 v[84:85], v[72:73]
	s_waitcnt vmcnt(2)
	v_mov_b64_e32 v[88:89], v[76:77]
	s_waitcnt vmcnt(1)
	v_mov_b64_e32 v[92:93], v[80:81]
	s_waitcnt vmcnt(0)
	v_mov_b64_e32 v[96:97], v[68:69]
	v_mov_b32_e32 v48, v2
	v_mov_b32_e32 v49, v2
	v_mov_b32_e32 v50, v2
	v_mov_b32_e32 v51, v2
	v_mov_b32_e32 v52, v2
	v_mov_b32_e32 v53, v2
	v_mov_b32_e32 v54, v2
	v_mov_b32_e32 v55, v2
	v_mov_b32_e32 v56, v2
	v_mov_b32_e32 v57, v2
	v_mov_b32_e32 v58, v2
	v_mov_b32_e32 v59, v2
	v_mov_b32_e32 v60, v2
	v_mov_b32_e32 v61, v2
	v_mov_b32_e32 v62, v2
	v_mov_b32_e32 v63, v2
	v_mov_b32_e32 v64, v2
	v_mov_b32_e32 v65, v2
	v_mov_b64_e32 v[82:83], v[70:71]
	v_mov_b64_e32 v[86:87], v[74:75]
	v_mov_b64_e32 v[90:91], v[78:79]
	v_mov_b64_e32 v[94:95], v[66:67]
	s_cmpk_eq_i32 s10, 0xe0
	s_movk_i32 s8, 0x70
	s_cbranch_scc1 .LBB0_334

.LBB0_349:
	s_add_i32 s8, s48, -15
	global_load_dwordx4 v[70:73], v[112:113], off
	global_load_dwordx4 v[74:77], v[114:115], off
	global_load_dwordx4 v[78:81], v[116:117], off
	global_load_dwordx4 v[66:69], v[118:119], off
	v_mov_b32_e32 v2, 0
	s_andn2_b64 vcc, exec, s[10:11]
	v_mov_b32_e32 v44, 0
	v_mov_b32_e32 v45, 0
	v_mov_b32_e32 v46, 0
	v_mov_b32_e32 v47, 0
	s_cbranch_vccnz .LBB0_351
	v_add_u32_e32 v3, s8, v195
	v_mad_i64_i32 v[4:5], s[10:11], v3, s37, v[132:133]
	v_add_u32_e32 v3, s8, v199
	v_mad_i64_i32 v[6:7], s[10:11], v3, s37, v[132:133]
	v_add_u32_e32 v3, s8, v200
	global_load_dwordx4 v[36:39], v[4:5], off offset:512
	global_load_dwordx4 v[40:43], v[6:7], off offset:512
	v_mad_i64_i32 v[4:5], s[10:11], v3, s37, v[132:133]
	global_load_dwordx4 v[44:47], v[4:5], off offset:512
	v_add_u32_e32 v3, v157, v198
	v_mov_b32_e32 v52, v3
.LBB0_351:
	v_add_u32_e32 v53, v157, v201
	s_or_b64 s[10:11], s[0:1], s[6:7]
	v_mov_b32_e32 v3, 0
	v_mov_b32_e32 v4, 0
	v_mov_b32_e32 v5, 0
	s_and_saveexec_b64 s[6:7], s[10:11]
	s_cbranch_execz .LBB0_353
	v_add_u32_e32 v2, s8, v202
	v_mad_i64_i32 v[2:3], s[10:11], v2, s37, v[132:133]
	global_load_dwordx4 v[2:5], v[2:3], off offset:512
.LBB0_353:
	s_or_b64 exec, exec, s[6:7]
	v_add_u32_e32 v6, s8, v204
	v_add_u32_e32 v8, s8, v205
	v_mad_i64_i32 v[6:7], s[6:7], v6, s37, v[132:133]
	v_mad_i64_i32 v[12:13], s[6:7], v8, s37, v[132:133]
	global_load_dwordx4 v[8:11], v[6:7], off offset:512
	s_nop 0
	global_load_dwordx4 v[12:15], v[12:13], off offset:512
	v_add_u32_e32 v6, s8, v206
	v_add_u32_e32 v16, s8, v207
	v_mad_i64_i32 v[6:7], s[6:7], v6, s37, v[132:133]
	v_mad_i64_i32 v[20:21], s[6:7], v16, s37, v[132:133]
	global_load_dwordx4 v[16:19], v[6:7], off offset:512
	s_nop 0
	global_load_dwordx4 v[20:23], v[20:21], off offset:512
	v_add_u32_e32 v6, s8, v208
	v_add_u32_e32 v24, s8, v209
	v_mad_i64_i32 v[6:7], s[6:7], v6, s37, v[132:133]
	v_mad_i64_i32 v[28:29], s[6:7], v24, s37, v[132:133]
	global_load_dwordx4 v[24:27], v[6:7], off offset:512
	s_nop 0
	global_load_dwordx4 v[28:31], v[28:29], off offset:512
	v_add_u32_e32 v6, s8, v210
	v_mad_i64_i32 v[6:7], s[6:7], v6, s37, v[132:133]
	global_load_dwordx4 v[32:35], v[6:7], off offset:512
	s_and_saveexec_b64 s[6:7], s[4:5]
	v_add_u32_e32 v48, s8, v211
	v_mad_i64_i32 v[48:49], s[10:11], v48, s37, v[132:133]
	global_load_dwordx4 v[48:51], v[48:49], off offset:512
	s_or_b64 exec, exec, s[6:7]
	v_add_u32_e32 v6, v157, v203
	s_waitcnt vmcnt(0)
	ds_write_b128 v53, v[44:47]
	s_cmp_eq_u32 s28, 0
	s_cbranch_scc1 .Lpsm_1
	ds_write_b128 v52, v[36:39]
	ds_write_b128 v52, v[40:43] offset:1088

.LBB0_355:
	s_or_b64 exec, exec, s[6:7]
	s_waitcnt lgkmcnt(0)
	v_or_b32_e32 v2, s28, v1
	v_min_u32_e32 v3, 7, v2
	v_add_u32_e32 v3, 1, v3
	v_cvt_f32_ubyte0_e32 v3, v3
	v_div_scale_f32 v4, s[6:7], v3, v3, 1.0
	v_rcp_f32_e32 v5, v4
	s_ashr_i32 s8, s30, 6
	s_mul_i32 s10, s8, 15
	v_cmp_lt_u32_e64 s[6:7], s41, v2
	v_fma_f32 v6, -v4, v5, 1.0
	v_fmac_f32_e32 v5, v6, v5
	v_div_scale_f32 v6, vcc, 1.0, v3, 1.0
	v_mul_f32_e32 v7, v6, v5
	v_fma_f32 v8, -v4, v7, v6
	v_fmac_f32_e32 v7, v8, v5
	v_fma_f32 v4, -v4, v7, v6
	v_div_fmas_f32 v4, v4, v5, v7
	v_div_fixup_f32 v159, v4, v3, 1.0
	s_ashr_i32 s11, s10, 31
	v_add_u32_e32 v2, 0xfffff80f, v2
	v_mov_b32_e32 v3, v155
	v_lshl_add_u64 v[2:3], v[2:3], 0, s[10:11]
	v_lshlrev_b64 v[2:3], 11, v[2:3]
	v_lshl_add_u64 v[2:3], s[70:71], 0, v[2:3]
	v_mov_b32_e32 v163, v155
	v_lshl_add_u64 v[2:3], v[2:3], 0, v[162:163]
	v_lshl_add_u64 v[192:193], v[2:3], 0, s[20:21]
	v_mov_b32_e32 v2, 0
	s_mov_b32 s49, 0
	s_mov_b64 s[10:11], 0
	v_mov_b32_e32 v3, v2
	v_mov_b32_e32 v4, v2
	v_mov_b32_e32 v5, v2
	v_mov_b32_e32 v6, v2
	v_mov_b32_e32 v7, v2
	v_mov_b32_e32 v8, v2
	v_mov_b32_e32 v9, v2
	v_mov_b32_e32 v10, v2
	v_mov_b32_e32 v11, v2
	v_mov_b32_e32 v12, v2
	v_mov_b32_e32 v13, v2
	v_mov_b32_e32 v14, v2
	v_mov_b32_e32 v15, v2
	v_mov_b32_e32 v16, v2
	v_mov_b32_e32 v17, v2
	v_mov_b32_e32 v18, v2
	v_mov_b32_e32 v19, v2
	v_mov_b32_e32 v20, v2
	v_mov_b32_e32 v21, v2
	v_mov_b32_e32 v22, v2
	v_mov_b32_e32 v23, v2
	v_mov_b32_e32 v24, v2
	v_mov_b32_e32 v25, v2
	v_mov_b32_e32 v26, v2
	v_mov_b32_e32 v27, v2
	v_mov_b32_e32 v28, v2
	v_mov_b32_e32 v29, v2
	v_mov_b32_e32 v30, v2
	v_mov_b32_e32 v31, v2
	v_mov_b32_e32 v32, v2
	v_mov_b32_e32 v33, v2
	v_mov_b32_e32 v34, v2
	v_mov_b32_e32 v35, v2
	v_mov_b32_e32 v36, v2
	v_mov_b32_e32 v37, v2
	v_mov_b32_e32 v38, v2
	v_mov_b32_e32 v39, v2
	v_mov_b32_e32 v40, v2
	v_mov_b32_e32 v41, v2
	v_mov_b32_e32 v42, v2
	v_mov_b32_e32 v43, v2
	v_mov_b32_e32 v44, v2
	v_mov_b32_e32 v45, v2
	v_mov_b32_e32 v46, v2
	v_mov_b32_e32 v47, v2
	s_waitcnt vmcnt(3)
	v_mov_b64_e32 v[84:85], v[72:73]
	s_waitcnt vmcnt(2)
	v_mov_b64_e32 v[88:89], v[76:77]
	s_waitcnt vmcnt(1)
	v_mov_b64_e32 v[92:93], v[80:81]
	s_waitcnt vmcnt(0)
	v_mov_b64_e32 v[96:97], v[68:69]
	v_mov_b32_e32 v48, v2
	v_mov_b32_e32 v49, v2
	v_mov_b32_e32 v50, v2
	v_mov_b32_e32 v51, v2
	v_mov_b32_e32 v52, v2
	v_mov_b32_e32 v53, v2
	v_mov_b32_e32 v54, v2
	v_mov_b32_e32 v55, v2
	v_mov_b32_e32 v56, v2
	v_mov_b32_e32 v57, v2
	v_mov_b32_e32 v58, v2
	v_mov_b32_e32 v59, v2
	v_mov_b32_e32 v60, v2
	v_mov_b32_e32 v61, v2
	v_mov_b32_e32 v62, v2
	v_mov_b32_e32 v63, v2
	v_mov_b32_e32 v64, v2
	v_mov_b32_e32 v65, v2
	v_mov_b64_e32 v[82:83], v[70:71]
	v_mov_b64_e32 v[86:87], v[74:75]
	v_mov_b64_e32 v[90:91], v[78:79]
	v_mov_b64_e32 v[94:95], v[66:67]
	s_cmpk_eq_i32 s10, 0xe0
	s_movk_i32 s8, 0x70
	s_cbranch_scc1 .LBB0_357

.LBB0_373:
	s_add_i32 s8, s48, -15
	global_load_dwordx4 v[70:73], v[122:123], off
	global_load_dwordx4 v[74:77], v[124:125], off
	global_load_dwordx4 v[78:81], v[126:127], off
	global_load_dwordx4 v[66:69], v[128:129], off
	v_mov_b32_e32 v2, 0
	s_andn2_b64 vcc, exec, s[10:11]
	v_mov_b32_e32 v44, 0
	v_mov_b32_e32 v45, 0
	v_mov_b32_e32 v46, 0
	v_mov_b32_e32 v47, 0
	s_cbranch_vccnz .LBB0_375
	v_add_u32_e32 v3, s8, v195
	v_mad_i64_i32 v[4:5], s[10:11], v3, s37, v[132:133]
	v_add_u32_e32 v3, s8, v199
	v_mad_i64_i32 v[6:7], s[10:11], v3, s37, v[132:133]
	v_add_u32_e32 v3, s8, v200
	global_load_dwordx4 v[36:39], v[4:5], off offset:256
	global_load_dwordx4 v[40:43], v[6:7], off offset:256
	v_mad_i64_i32 v[4:5], s[10:11], v3, s37, v[132:133]
	global_load_dwordx4 v[44:47], v[4:5], off offset:256
	v_add_u32_e32 v3, v157, v198
	v_mov_b32_e32 v52, v3
.LBB0_375:
	v_add_u32_e32 v53, v157, v201
	s_or_b64 s[10:11], s[0:1], s[6:7]
	v_mov_b32_e32 v3, 0
	v_mov_b32_e32 v4, 0
	v_mov_b32_e32 v5, 0
	s_and_saveexec_b64 s[6:7], s[10:11]
	s_cbranch_execz .LBB0_377
	v_add_u32_e32 v2, s8, v202
	v_mad_i64_i32 v[2:3], s[10:11], v2, s37, v[132:133]
	global_load_dwordx4 v[2:5], v[2:3], off offset:256
.LBB0_377:
	s_or_b64 exec, exec, s[6:7]
	v_add_u32_e32 v6, s8, v204
	v_add_u32_e32 v8, s8, v205
	v_mad_i64_i32 v[6:7], s[6:7], v6, s37, v[132:133]
	v_mad_i64_i32 v[12:13], s[6:7], v8, s37, v[132:133]
	global_load_dwordx4 v[8:11], v[6:7], off offset:256
	s_nop 0
	global_load_dwordx4 v[12:15], v[12:13], off offset:256
	v_add_u32_e32 v6, s8, v206
	v_add_u32_e32 v16, s8, v207
	v_mad_i64_i32 v[6:7], s[6:7], v6, s37, v[132:133]
	v_mad_i64_i32 v[20:21], s[6:7], v16, s37, v[132:133]
	global_load_dwordx4 v[16:19], v[6:7], off offset:256
	s_nop 0
	global_load_dwordx4 v[20:23], v[20:21], off offset:256
	v_add_u32_e32 v6, s8, v208
	v_add_u32_e32 v24, s8, v209
	v_mad_i64_i32 v[6:7], s[6:7], v6, s37, v[132:133]
	v_mad_i64_i32 v[28:29], s[6:7], v24, s37, v[132:133]
	global_load_dwordx4 v[24:27], v[6:7], off offset:256
	s_nop 0
	global_load_dwordx4 v[28:31], v[28:29], off offset:256
	v_add_u32_e32 v6, s8, v210
	v_mad_i64_i32 v[6:7], s[6:7], v6, s37, v[132:133]
	global_load_dwordx4 v[32:35], v[6:7], off offset:256
	s_and_saveexec_b64 s[6:7], s[4:5]
	v_add_u32_e32 v48, s8, v211
	v_mad_i64_i32 v[48:49], s[10:11], v48, s37, v[132:133]
	global_load_dwordx4 v[48:51], v[48:49], off offset:256
	s_or_b64 exec, exec, s[6:7]
	v_add_u32_e32 v6, v157, v203
	s_waitcnt vmcnt(0)
	ds_write_b128 v53, v[44:47]
	s_cmp_eq_u32 s28, 0
	s_cbranch_scc1 .Lpsm_2
	ds_write_b128 v52, v[36:39]
	ds_write_b128 v52, v[40:43] offset:1088

.LBB0_379:
	s_or_b64 exec, exec, s[6:7]
	s_waitcnt lgkmcnt(0)
	v_or_b32_e32 v2, s28, v1
	v_min_u32_e32 v3, 3, v2
	v_add_u32_e32 v3, 1, v3
	v_cvt_f32_ubyte0_e32 v3, v3
	v_div_scale_f32 v4, s[6:7], v3, v3, 1.0
	v_rcp_f32_e32 v5, v4
	s_ashr_i32 s8, s30, 6
	s_mul_i32 s10, s8, 15
	v_cmp_lt_u32_e64 s[6:7], s41, v2
	v_fma_f32 v6, -v4, v5, 1.0
	v_fmac_f32_e32 v5, v6, v5
	v_div_scale_f32 v6, vcc, 1.0, v3, 1.0
	v_mul_f32_e32 v7, v6, v5
	v_fma_f32 v8, -v4, v7, v6
	v_fmac_f32_e32 v7, v8, v5
	v_fma_f32 v4, -v4, v7, v6
	v_div_fmas_f32 v4, v4, v5, v7
	v_div_fixup_f32 v159, v4, v3, 1.0
	s_ashr_i32 s11, s10, 31
	v_add_u32_e32 v2, 0xfffff80f, v2
	v_mov_b32_e32 v3, v155
	v_lshl_add_u64 v[2:3], v[2:3], 0, s[10:11]
	v_lshlrev_b64 v[2:3], 11, v[2:3]
	v_lshl_add_u64 v[2:3], s[70:71], 0, v[2:3]
	v_mov_b32_e32 v163, v155
	v_lshl_add_u64 v[2:3], v[2:3], 0, v[162:163]
	v_lshl_add_u64 v[190:191], v[2:3], 0, s[24:25]
	v_mov_b32_e32 v2, 0
	s_mov_b32 s49, 0
	s_mov_b64 s[10:11], 0
	v_mov_b32_e32 v3, v2
	v_mov_b32_e32 v4, v2
	v_mov_b32_e32 v5, v2
	v_mov_b32_e32 v6, v2
	v_mov_b32_e32 v7, v2
	v_mov_b32_e32 v8, v2
	v_mov_b32_e32 v9, v2
	v_mov_b32_e32 v10, v2
	v_mov_b32_e32 v11, v2
	v_mov_b32_e32 v12, v2
	v_mov_b32_e32 v13, v2
	v_mov_b32_e32 v14, v2
	v_mov_b32_e32 v15, v2
	v_mov_b32_e32 v16, v2
	v_mov_b32_e32 v17, v2
	v_mov_b32_e32 v18, v2
	v_mov_b32_e32 v19, v2
	v_mov_b32_e32 v20, v2
	v_mov_b32_e32 v21, v2
	v_mov_b32_e32 v22, v2
	v_mov_b32_e32 v23, v2
	v_mov_b32_e32 v24, v2
	v_mov_b32_e32 v25, v2
	v_mov_b32_e32 v26, v2
	v_mov_b32_e32 v27, v2
	v_mov_b32_e32 v28, v2
	v_mov_b32_e32 v29, v2
	v_mov_b32_e32 v30, v2
	v_mov_b32_e32 v31, v2
	v_mov_b32_e32 v32, v2
	v_mov_b32_e32 v33, v2
	v_mov_b32_e32 v34, v2
	v_mov_b32_e32 v35, v2
	v_mov_b32_e32 v36, v2
	v_mov_b32_e32 v37, v2
	v_mov_b32_e32 v38, v2
	v_mov_b32_e32 v39, v2
	v_mov_b32_e32 v40, v2
	v_mov_b32_e32 v41, v2
	v_mov_b32_e32 v42, v2
	v_mov_b32_e32 v43, v2
	v_mov_b32_e32 v44, v2
	v_mov_b32_e32 v45, v2
	v_mov_b32_e32 v46, v2
	v_mov_b32_e32 v47, v2
	s_waitcnt vmcnt(3)
	v_mov_b64_e32 v[84:85], v[72:73]
	s_waitcnt vmcnt(2)
	v_mov_b64_e32 v[88:89], v[76:77]
	s_waitcnt vmcnt(1)
	v_mov_b64_e32 v[92:93], v[80:81]
	s_waitcnt vmcnt(0)
	v_mov_b64_e32 v[96:97], v[68:69]
	v_mov_b32_e32 v48, v2
	v_mov_b32_e32 v49, v2
	v_mov_b32_e32 v50, v2
	v_mov_b32_e32 v51, v2
	v_mov_b32_e32 v52, v2
	v_mov_b32_e32 v53, v2
	v_mov_b32_e32 v54, v2
	v_mov_b32_e32 v55, v2
	v_mov_b32_e32 v56, v2
	v_mov_b32_e32 v57, v2
	v_mov_b32_e32 v58, v2
	v_mov_b32_e32 v59, v2
	v_mov_b32_e32 v60, v2
	v_mov_b32_e32 v61, v2
	v_mov_b32_e32 v62, v2
	v_mov_b32_e32 v63, v2
	v_mov_b32_e32 v64, v2
	v_mov_b32_e32 v65, v2
	v_mov_b64_e32 v[82:83], v[70:71]
	v_mov_b64_e32 v[86:87], v[74:75]
	v_mov_b64_e32 v[90:91], v[78:79]
	v_mov_b64_e32 v[94:95], v[66:67]
	s_cmpk_eq_i32 s10, 0xe0
	s_movk_i32 s8, 0x70
	s_cbranch_scc1 .LBB0_381

.LBB0_397:
	s_add_i32 s8, s48, -15
	global_load_dwordx4 v[70:73], v[110:111], off
	global_load_dwordx4 v[74:77], v[134:135], off
	global_load_dwordx4 v[78:81], v[136:137], off
	global_load_dwordx4 v[66:69], v[138:139], off
	v_mov_b32_e32 v2, 0
	s_andn2_b64 vcc, exec, s[6:7]
	v_mov_b32_e32 v44, 0
	v_mov_b32_e32 v45, 0
	v_mov_b32_e32 v46, 0
	v_mov_b32_e32 v47, 0
	s_cbranch_vccnz .LBB0_399
	v_add_u32_e32 v4, s8, v195
	v_mad_i64_i32 v[4:5], s[6:7], v4, s37, v[132:133]
	v_add_u32_e32 v6, s8, v199
	v_mad_i64_i32 v[6:7], s[6:7], v6, s37, v[132:133]
	global_load_dwordx4 v[36:39], v[4:5], off
	global_load_dwordx4 v[40:43], v[6:7], off
	v_add_u32_e32 v4, s8, v200
	v_mad_i64_i32 v[4:5], s[6:7], v4, s37, v[132:133]
	global_load_dwordx4 v[44:47], v[4:5], off
	v_mov_b32_e32 v52, v3
.LBB0_399:
	v_add_u32_e32 v53, v157, v201
	s_or_b64 s[6:7], s[0:1], s[2:3]
	v_mov_b32_e32 v3, 0
	v_mov_b32_e32 v4, 0
	v_mov_b32_e32 v5, 0
	s_and_saveexec_b64 s[2:3], s[6:7]
	s_cbranch_execz .LBB0_401
	v_add_u32_e32 v2, s8, v202
	v_mad_i64_i32 v[2:3], s[6:7], v2, s37, v[132:133]
	global_load_dwordx4 v[2:5], v[2:3], off
.LBB0_401:
	s_or_b64 exec, exec, s[2:3]
	v_add_u32_e32 v6, s8, v204
	v_add_u32_e32 v8, s8, v205
	v_mad_i64_i32 v[6:7], s[2:3], v6, s37, v[132:133]
	v_mad_i64_i32 v[12:13], s[2:3], v8, s37, v[132:133]
	global_load_dwordx4 v[8:11], v[6:7], off
	s_nop 0
	global_load_dwordx4 v[12:15], v[12:13], off
	v_add_u32_e32 v6, s8, v206
	v_add_u32_e32 v16, s8, v207
	v_mad_i64_i32 v[6:7], s[2:3], v6, s37, v[132:133]
	v_mad_i64_i32 v[20:21], s[2:3], v16, s37, v[132:133]
	global_load_dwordx4 v[16:19], v[6:7], off
	s_nop 0
	global_load_dwordx4 v[20:23], v[20:21], off
	v_add_u32_e32 v6, s8, v208
	v_add_u32_e32 v24, s8, v209
	v_mad_i64_i32 v[6:7], s[2:3], v6, s37, v[132:133]
	v_mad_i64_i32 v[28:29], s[2:3], v24, s37, v[132:133]
	global_load_dwordx4 v[24:27], v[6:7], off
	s_nop 0
	global_load_dwordx4 v[28:31], v[28:29], off
	v_add_u32_e32 v6, s8, v210
	v_mad_i64_i32 v[6:7], s[2:3], v6, s37, v[132:133]
	global_load_dwordx4 v[32:35], v[6:7], off
	s_and_saveexec_b64 s[2:3], s[4:5]
	v_add_u32_e32 v48, s8, v211
	v_mad_i64_i32 v[48:49], s[6:7], v48, s37, v[132:133]
	global_load_dwordx4 v[48:51], v[48:49], off
	s_or_b64 exec, exec, s[2:3]
	v_add_u32_e32 v6, v157, v203
	s_waitcnt vmcnt(0)
	ds_write_b128 v53, v[44:47]
	s_cmp_eq_u32 s28, 0
	s_cbranch_scc1 .Lpsm_3
	ds_write_b128 v52, v[36:39]
	ds_write_b128 v52, v[40:43] offset:1088
.Lpsm_3:
	ds_write_b128 v6, v[2:5]
	ds_write_b128 v6, v[8:11] offset:1088
	ds_write_b128 v6, v[12:15] offset:2176
	ds_write_b128 v6, v[16:19] offset:3264
	ds_write_b128 v6, v[20:23] offset:4352
	ds_write_b128 v6, v[24:27] offset:5440
	ds_write_b128 v6, v[28:31] offset:6528
	ds_write_b128 v6, v[32:35] offset:7616
	s_and_saveexec_b64 s[2:3], s[4:5]
	s_cbranch_execz .LBB0_403
	ds_write_b128 v6, v[48:51] offset:8704
.LBB0_403:
	s_or_b64 exec, exec, s[2:3]
	s_waitcnt lgkmcnt(0)
	s_ashr_i32 s2, s30, 6
	v_or_b32_e32 v2, s28, v1
	s_mul_i32 s2, s2, 15
	v_cmp_eq_u32_e32 vcc, 0, v2
	v_cmp_lt_u32_e64 s[6:7], s41, v2
	s_ashr_i32 s3, s2, 31
	v_add_u32_e32 v2, 0xfffff80f, v2
	v_mov_b32_e32 v3, v155
	v_lshl_add_u64 v[2:3], v[2:3], 0, s[2:3]
	v_lshlrev_b64 v[2:3], 11, v[2:3]
	v_lshl_add_u64 v[184:185], v[140:141], 0, v[2:3]
	v_mov_b32_e32 v2, 0
	s_mov_b32 s28, 0
	v_cndmask_b32_e64 v159, 0.5, 1.0, vcc
	s_mov_b64 s[2:3], 0
	v_mov_b32_e32 v3, v2
	v_mov_b32_e32 v4, v2
	v_mov_b32_e32 v5, v2
	v_mov_b32_e32 v6, v2
	v_mov_b32_e32 v7, v2
	v_mov_b32_e32 v8, v2
	v_mov_b32_e32 v9, v2
	v_mov_b32_e32 v10, v2
	v_mov_b32_e32 v11, v2
	v_mov_b32_e32 v12, v2
	v_mov_b32_e32 v13, v2
	v_mov_b32_e32 v14, v2
	v_mov_b32_e32 v15, v2
	v_mov_b32_e32 v16, v2
	v_mov_b32_e32 v17, v2
	v_mov_b32_e32 v18, v2
	v_mov_b32_e32 v19, v2
	v_mov_b32_e32 v20, v2
	v_mov_b32_e32 v21, v2
	v_mov_b32_e32 v22, v2
	v_mov_b32_e32 v23, v2
	v_mov_b32_e32 v24, v2
	v_mov_b32_e32 v25, v2
	v_mov_b32_e32 v26, v2
	v_mov_b32_e32 v27, v2
	v_mov_b32_e32 v28, v2
	v_mov_b32_e32 v29, v2
	v_mov_b32_e32 v30, v2
	v_mov_b32_e32 v31, v2
	v_mov_b32_e32 v32, v2
	v_mov_b32_e32 v33, v2
	v_mov_b32_e32 v34, v2
	v_mov_b32_e32 v35, v2
	v_mov_b32_e32 v36, v2
	v_mov_b32_e32 v37, v2
	v_mov_b32_e32 v38, v2
	v_mov_b32_e32 v39, v2
	v_mov_b32_e32 v40, v2
	v_mov_b32_e32 v41, v2
	v_mov_b32_e32 v42, v2
	v_mov_b32_e32 v43, v2
	v_mov_b32_e32 v44, v2
	v_mov_b32_e32 v45, v2
	v_mov_b32_e32 v46, v2
	v_mov_b32_e32 v47, v2
	v_mov_b32_e32 v48, v2
	v_mov_b32_e32 v49, v2
	v_mov_b32_e32 v50, v2
	v_mov_b32_e32 v51, v2
	v_mov_b32_e32 v52, v2
	v_mov_b32_e32 v53, v2
	v_mov_b32_e32 v54, v2
	v_mov_b32_e32 v55, v2
	v_mov_b32_e32 v56, v2
	v_mov_b32_e32 v57, v2
	v_mov_b32_e32 v58, v2
	v_mov_b32_e32 v59, v2
	v_mov_b32_e32 v60, v2
	v_mov_b32_e32 v61, v2
	v_mov_b32_e32 v62, v2
	v_mov_b32_e32 v63, v2
	s_waitcnt vmcnt(3)
	v_mov_b64_e32 v[84:85], v[72:73]
	s_waitcnt vmcnt(2)
	v_mov_b64_e32 v[88:89], v[76:77]
	s_waitcnt vmcnt(1)
	v_mov_b64_e32 v[92:93], v[80:81]
	s_waitcnt vmcnt(0)
	v_mov_b64_e32 v[96:97], v[68:69]
	v_mov_b32_e32 v64, v2
	v_mov_b32_e32 v65, v2
	v_mov_b64_e32 v[82:83], v[70:71]
	v_mov_b64_e32 v[86:87], v[74:75]
	v_mov_b64_e32 v[90:91], v[78:79]
	v_mov_b64_e32 v[94:95], v[66:67]
	s_cmpk_eq_i32 s2, 0xe0
	s_movk_i32 s8, 0x70
	s_cbranch_scc1 .LBB0_405

.LBB0_424:
	s_add_i32 s8, s44, -15
	global_load_dwordx4 v[70:73], v[144:145], off
	global_load_dwordx4 v[74:77], v[146:147], off
	global_load_dwordx4 v[78:81], v[148:149], off
	global_load_dwordx4 v[66:69], v[150:151], off
	v_mov_b32_e32 v2, 0
	s_andn2_b64 vcc, exec, s[10:11]
	v_mov_b32_e32 v44, 0
	v_mov_b32_e32 v45, 0
	v_mov_b32_e32 v46, 0
	v_mov_b32_e32 v47, 0
	s_cbranch_vccnz .LBB0_426
	v_add_u32_e32 v3, s8, v195
	v_mad_i64_i32 v[4:5], s[10:11], v3, s30, v[132:133]
	v_add_u32_e32 v3, s8, v199
	v_mad_i64_i32 v[6:7], s[10:11], v3, s30, v[132:133]
	v_add_u32_e32 v3, s8, v200
	global_load_dwordx4 v[36:39], v[4:5], off offset:768
	global_load_dwordx4 v[40:43], v[6:7], off offset:768
	v_mad_i64_i32 v[4:5], s[10:11], v3, s30, v[132:133]
	global_load_dwordx4 v[44:47], v[4:5], off offset:768
	v_add_u32_e32 v3, v184, v198
	v_mov_b32_e32 v52, v3
.LBB0_426:
	v_add_u32_e32 v53, v184, v201
	s_or_b64 s[10:11], s[0:1], s[6:7]
	v_mov_b32_e32 v3, 0
	v_mov_b32_e32 v4, 0
	v_mov_b32_e32 v5, 0
	s_and_saveexec_b64 s[6:7], s[10:11]
	s_cbranch_execz .LBB0_428
	v_add_u32_e32 v2, s8, v202
	v_mad_i64_i32 v[2:3], s[10:11], v2, s30, v[132:133]
	global_load_dwordx4 v[2:5], v[2:3], off offset:768
.LBB0_428:
	s_or_b64 exec, exec, s[6:7]
	v_add_u32_e32 v6, s8, v204
	v_add_u32_e32 v8, s8, v205
	v_mad_i64_i32 v[6:7], s[6:7], v6, s30, v[132:133]
	v_mad_i64_i32 v[12:13], s[6:7], v8, s30, v[132:133]
	global_load_dwordx4 v[8:11], v[6:7], off offset:768
	s_nop 0
	global_load_dwordx4 v[12:15], v[12:13], off offset:768
	v_add_u32_e32 v6, s8, v206
	v_add_u32_e32 v16, s8, v207
	v_mad_i64_i32 v[6:7], s[6:7], v6, s30, v[132:133]
	v_mad_i64_i32 v[20:21], s[6:7], v16, s30, v[132:133]
	global_load_dwordx4 v[16:19], v[6:7], off offset:768
	s_nop 0
	global_load_dwordx4 v[20:23], v[20:21], off offset:768
	v_add_u32_e32 v6, s8, v208
	v_add_u32_e32 v24, s8, v209
	v_mad_i64_i32 v[6:7], s[6:7], v6, s30, v[132:133]
	v_mad_i64_i32 v[28:29], s[6:7], v24, s30, v[132:133]
	global_load_dwordx4 v[24:27], v[6:7], off offset:768
	s_nop 0
	global_load_dwordx4 v[28:31], v[28:29], off offset:768
	v_add_u32_e32 v6, s8, v210
	v_mad_i64_i32 v[6:7], s[6:7], v6, s30, v[132:133]
	global_load_dwordx4 v[32:35], v[6:7], off offset:768
	s_and_saveexec_b64 s[6:7], s[4:5]
	v_add_u32_e32 v48, s8, v211
	v_mad_i64_i32 v[48:49], s[10:11], v48, s30, v[132:133]
	global_load_dwordx4 v[48:51], v[48:49], off offset:768
	s_or_b64 exec, exec, s[6:7]
	v_add_u32_e32 v6, v184, v203
	s_waitcnt vmcnt(0)
	ds_write_b128 v53, v[44:47]
	s_cmp_eq_u32 s28, 0
	s_cbranch_scc1 .Lpsm_4
	ds_write_b128 v52, v[36:39]
	ds_write_b128 v52, v[40:43] offset:1088

.LBB0_430:
	s_or_b64 exec, exec, s[6:7]
	s_waitcnt lgkmcnt(0)
	v_or_b32_e32 v2, s28, v1
	v_min_u32_e32 v3, 15, v2
	v_add_u32_e32 v3, 1, v3
	v_cvt_f32_ubyte0_e32 v3, v3
	v_div_scale_f32 v4, s[6:7], v3, v3, 1.0
	v_rcp_f32_e32 v5, v4
	s_ashr_i32 s8, s45, 6
	s_mul_i32 s10, s8, 15
	s_ashr_i32 s11, s10, 31
	v_fma_f32 v6, -v4, v5, 1.0
	v_fmac_f32_e32 v5, v6, v5
	v_div_scale_f32 v6, vcc, 1.0, v3, 1.0
	v_mul_f32_e32 v7, v6, v5
	v_fma_f32 v8, -v4, v7, v6
	v_fmac_f32_e32 v7, v8, v5
	v_fma_f32 v4, -v4, v7, v6
	v_div_fmas_f32 v4, v4, v5, v7
	v_add_u32_e32 v156, 0xfffff80f, v2
	v_div_fixup_f32 v155, v4, v3, 1.0
	v_cmp_lt_u32_e64 s[6:7], s36, v2
	v_lshl_add_u64 v[2:3], v[156:157], 0, s[10:11]
	v_lshlrev_b64 v[2:3], 11, v[2:3]
	v_lshl_add_u64 v[2:3], s[70:71], 0, v[2:3]
	v_mov_b32_e32 v161, v157
	v_lshl_add_u64 v[2:3], v[2:3], 0, v[160:161]
	v_lshl_add_u64 v[182:183], v[2:3], 0, s[16:17]
	v_mov_b32_e32 v2, 0
	s_mov_b32 s47, 0
	s_mov_b64 s[10:11], 0
	v_mov_b32_e32 v3, v2
	v_mov_b32_e32 v4, v2
	v_mov_b32_e32 v5, v2
	v_mov_b32_e32 v6, v2
	v_mov_b32_e32 v7, v2
	v_mov_b32_e32 v8, v2
	v_mov_b32_e32 v9, v2
	v_mov_b32_e32 v10, v2
	v_mov_b32_e32 v11, v2
	v_mov_b32_e32 v12, v2
	v_mov_b32_e32 v13, v2
	v_mov_b32_e32 v14, v2
	v_mov_b32_e32 v15, v2
	v_mov_b32_e32 v16, v2
	v_mov_b32_e32 v17, v2
	v_mov_b32_e32 v18, v2
	v_mov_b32_e32 v19, v2
	v_mov_b32_e32 v20, v2
	v_mov_b32_e32 v21, v2
	v_mov_b32_e32 v22, v2
	v_mov_b32_e32 v23, v2
	v_mov_b32_e32 v24, v2
	v_mov_b32_e32 v25, v2
	v_mov_b32_e32 v26, v2
	v_mov_b32_e32 v27, v2
	v_mov_b32_e32 v28, v2
	v_mov_b32_e32 v29, v2
	v_mov_b32_e32 v30, v2
	v_mov_b32_e32 v31, v2
	v_mov_b32_e32 v32, v2
	v_mov_b32_e32 v33, v2
	v_mov_b32_e32 v34, v2
	v_mov_b32_e32 v35, v2
	v_mov_b32_e32 v36, v2
	v_mov_b32_e32 v37, v2
	v_mov_b32_e32 v38, v2
	v_mov_b32_e32 v39, v2
	v_mov_b32_e32 v40, v2
	v_mov_b32_e32 v41, v2
	v_mov_b32_e32 v42, v2
	v_mov_b32_e32 v43, v2
	v_mov_b32_e32 v44, v2
	v_mov_b32_e32 v45, v2
	v_mov_b32_e32 v46, v2
	v_mov_b32_e32 v47, v2
	v_mov_b32_e32 v48, v2
	s_waitcnt vmcnt(3)
	v_mov_b64_e32 v[84:85], v[72:73]
	s_waitcnt vmcnt(2)
	v_mov_b64_e32 v[88:89], v[76:77]
	s_waitcnt vmcnt(1)
	v_mov_b64_e32 v[92:93], v[80:81]
	s_waitcnt vmcnt(0)
	v_mov_b64_e32 v[96:97], v[68:69]
	v_mov_b32_e32 v49, v2
	v_mov_b32_e32 v50, v2
	v_mov_b32_e32 v51, v2
	v_mov_b32_e32 v52, v2
	v_mov_b32_e32 v53, v2
	v_mov_b32_e32 v54, v2
	v_mov_b32_e32 v55, v2
	v_mov_b32_e32 v56, v2
	v_mov_b32_e32 v57, v2
	v_mov_b32_e32 v58, v2
	v_mov_b32_e32 v59, v2
	v_mov_b32_e32 v60, v2
	v_mov_b32_e32 v61, v2
	v_mov_b32_e32 v62, v2
	v_mov_b32_e32 v63, v2
	v_mov_b32_e32 v64, v2
	v_mov_b32_e32 v65, v2
	v_mov_b64_e32 v[82:83], v[70:71]
	v_mov_b64_e32 v[86:87], v[74:75]
	v_mov_b64_e32 v[90:91], v[78:79]
	v_mov_b64_e32 v[94:95], v[66:67]
	s_cmpk_eq_i32 s10, 0xe0
	s_movk_i32 s8, 0x70
	s_cbranch_scc1 .LBB0_432

.LBB0_447:
	s_add_i32 s8, s44, -15
	global_load_dwordx4 v[70:73], v[112:113], off
	global_load_dwordx4 v[74:77], v[114:115], off
	global_load_dwordx4 v[78:81], v[116:117], off
	global_load_dwordx4 v[66:69], v[118:119], off
	v_mov_b32_e32 v2, 0
	s_andn2_b64 vcc, exec, s[10:11]
	v_mov_b32_e32 v44, 0
	v_mov_b32_e32 v45, 0
	v_mov_b32_e32 v46, 0
	v_mov_b32_e32 v47, 0
	s_cbranch_vccnz .LBB0_449
	v_add_u32_e32 v3, s8, v195
	v_mad_i64_i32 v[4:5], s[10:11], v3, s30, v[132:133]
	v_add_u32_e32 v3, s8, v199
	v_mad_i64_i32 v[6:7], s[10:11], v3, s30, v[132:133]
	v_add_u32_e32 v3, s8, v200
	global_load_dwordx4 v[36:39], v[4:5], off offset:512
	global_load_dwordx4 v[40:43], v[6:7], off offset:512
	v_mad_i64_i32 v[4:5], s[10:11], v3, s30, v[132:133]
	global_load_dwordx4 v[44:47], v[4:5], off offset:512
	v_add_u32_e32 v3, v184, v198
	v_mov_b32_e32 v52, v3
.LBB0_449:
	v_add_u32_e32 v53, v184, v201
	s_or_b64 s[10:11], s[0:1], s[6:7]
	v_mov_b32_e32 v3, 0
	v_mov_b32_e32 v4, 0
	v_mov_b32_e32 v5, 0
	s_and_saveexec_b64 s[6:7], s[10:11]
	s_cbranch_execz .LBB0_451
	v_add_u32_e32 v2, s8, v202
	v_mad_i64_i32 v[2:3], s[10:11], v2, s30, v[132:133]
	global_load_dwordx4 v[2:5], v[2:3], off offset:512
.LBB0_451:
	s_or_b64 exec, exec, s[6:7]
	v_add_u32_e32 v6, s8, v204
	v_add_u32_e32 v8, s8, v205
	v_mad_i64_i32 v[6:7], s[6:7], v6, s30, v[132:133]
	v_mad_i64_i32 v[12:13], s[6:7], v8, s30, v[132:133]
	global_load_dwordx4 v[8:11], v[6:7], off offset:512
	s_nop 0
	global_load_dwordx4 v[12:15], v[12:13], off offset:512
	v_add_u32_e32 v6, s8, v206
	v_add_u32_e32 v16, s8, v207
	v_mad_i64_i32 v[6:7], s[6:7], v6, s30, v[132:133]
	v_mad_i64_i32 v[20:21], s[6:7], v16, s30, v[132:133]
	global_load_dwordx4 v[16:19], v[6:7], off offset:512
	s_nop 0
	global_load_dwordx4 v[20:23], v[20:21], off offset:512
	v_add_u32_e32 v6, s8, v208
	v_add_u32_e32 v24, s8, v209
	v_mad_i64_i32 v[6:7], s[6:7], v6, s30, v[132:133]
	v_mad_i64_i32 v[28:29], s[6:7], v24, s30, v[132:133]
	global_load_dwordx4 v[24:27], v[6:7], off offset:512
	s_nop 0
	global_load_dwordx4 v[28:31], v[28:29], off offset:512
	v_add_u32_e32 v6, s8, v210
	v_mad_i64_i32 v[6:7], s[6:7], v6, s30, v[132:133]
	global_load_dwordx4 v[32:35], v[6:7], off offset:512
	s_and_saveexec_b64 s[6:7], s[4:5]
	v_add_u32_e32 v48, s8, v211
	v_mad_i64_i32 v[48:49], s[10:11], v48, s30, v[132:133]
	global_load_dwordx4 v[48:51], v[48:49], off offset:512
	s_or_b64 exec, exec, s[6:7]
	v_add_u32_e32 v6, v184, v203
	s_waitcnt vmcnt(0)
	ds_write_b128 v53, v[44:47]
	s_cmp_eq_u32 s28, 0
	s_cbranch_scc1 .Lpsm_5
	ds_write_b128 v52, v[36:39]
	ds_write_b128 v52, v[40:43] offset:1088

.LBB0_453:
	s_or_b64 exec, exec, s[6:7]
	s_waitcnt lgkmcnt(0)
	v_or_b32_e32 v2, s28, v1
	v_min_u32_e32 v3, 7, v2
	v_add_u32_e32 v3, 1, v3
	v_cvt_f32_ubyte0_e32 v3, v3
	v_div_scale_f32 v4, s[6:7], v3, v3, 1.0
	v_rcp_f32_e32 v5, v4
	s_ashr_i32 s8, s45, 6
	s_mul_i32 s10, s8, 15
	s_ashr_i32 s11, s10, 31
	v_fma_f32 v6, -v4, v5, 1.0
	v_fmac_f32_e32 v5, v6, v5
	v_div_scale_f32 v6, vcc, 1.0, v3, 1.0
	v_mul_f32_e32 v7, v6, v5
	v_fma_f32 v8, -v4, v7, v6
	v_fmac_f32_e32 v7, v8, v5
	v_fma_f32 v4, -v4, v7, v6
	v_div_fmas_f32 v4, v4, v5, v7
	v_add_u32_e32 v156, 0xfffff80f, v2
	v_div_fixup_f32 v155, v4, v3, 1.0
	v_cmp_lt_u32_e64 s[6:7], s36, v2
	v_lshl_add_u64 v[2:3], v[156:157], 0, s[10:11]
	v_lshlrev_b64 v[2:3], 11, v[2:3]
	v_lshl_add_u64 v[2:3], s[70:71], 0, v[2:3]
	v_mov_b32_e32 v161, v157
	v_lshl_add_u64 v[2:3], v[2:3], 0, v[160:161]
	v_lshl_add_u64 v[182:183], v[2:3], 0, s[20:21]
	v_mov_b32_e32 v2, 0
	s_mov_b32 s47, 0
	s_mov_b64 s[10:11], 0
	v_mov_b32_e32 v3, v2
	v_mov_b32_e32 v4, v2
	v_mov_b32_e32 v5, v2
	v_mov_b32_e32 v6, v2
	v_mov_b32_e32 v7, v2
	v_mov_b32_e32 v8, v2
	v_mov_b32_e32 v9, v2
	v_mov_b32_e32 v10, v2
	v_mov_b32_e32 v11, v2
	v_mov_b32_e32 v12, v2
	v_mov_b32_e32 v13, v2
	v_mov_b32_e32 v14, v2
	v_mov_b32_e32 v15, v2
	v_mov_b32_e32 v16, v2
	v_mov_b32_e32 v17, v2
	v_mov_b32_e32 v18, v2
	v_mov_b32_e32 v19, v2
	v_mov_b32_e32 v20, v2
	v_mov_b32_e32 v21, v2
	v_mov_b32_e32 v22, v2
	v_mov_b32_e32 v23, v2
	v_mov_b32_e32 v24, v2
	v_mov_b32_e32 v25, v2
	v_mov_b32_e32 v26, v2
	v_mov_b32_e32 v27, v2
	v_mov_b32_e32 v28, v2
	v_mov_b32_e32 v29, v2
	v_mov_b32_e32 v30, v2
	v_mov_b32_e32 v31, v2
	v_mov_b32_e32 v32, v2
	v_mov_b32_e32 v33, v2
	v_mov_b32_e32 v34, v2
	v_mov_b32_e32 v35, v2
	v_mov_b32_e32 v36, v2
	v_mov_b32_e32 v37, v2
	v_mov_b32_e32 v38, v2
	v_mov_b32_e32 v39, v2
	v_mov_b32_e32 v40, v2
	v_mov_b32_e32 v41, v2
	v_mov_b32_e32 v42, v2
	v_mov_b32_e32 v43, v2
	v_mov_b32_e32 v44, v2
	v_mov_b32_e32 v45, v2
	v_mov_b32_e32 v46, v2
	v_mov_b32_e32 v47, v2
	v_mov_b32_e32 v48, v2
	s_waitcnt vmcnt(3)
	v_mov_b64_e32 v[84:85], v[72:73]
	s_waitcnt vmcnt(2)
	v_mov_b64_e32 v[88:89], v[76:77]
	s_waitcnt vmcnt(1)
	v_mov_b64_e32 v[92:93], v[80:81]
	s_waitcnt vmcnt(0)
	v_mov_b64_e32 v[96:97], v[68:69]
	v_mov_b32_e32 v49, v2
	v_mov_b32_e32 v50, v2
	v_mov_b32_e32 v51, v2
	v_mov_b32_e32 v52, v2
	v_mov_b32_e32 v53, v2
	v_mov_b32_e32 v54, v2
	v_mov_b32_e32 v55, v2
	v_mov_b32_e32 v56, v2
	v_mov_b32_e32 v57, v2
	v_mov_b32_e32 v58, v2
	v_mov_b32_e32 v59, v2
	v_mov_b32_e32 v60, v2
	v_mov_b32_e32 v61, v2
	v_mov_b32_e32 v62, v2
	v_mov_b32_e32 v63, v2
	v_mov_b32_e32 v64, v2
	v_mov_b32_e32 v65, v2
	v_mov_b64_e32 v[82:83], v[70:71]
	v_mov_b64_e32 v[86:87], v[74:75]
	v_mov_b64_e32 v[90:91], v[78:79]
	v_mov_b64_e32 v[94:95], v[66:67]
	s_cmpk_eq_i32 s10, 0xe0
	s_movk_i32 s8, 0x70
	s_cbranch_scc1 .LBB0_455

.LBB0_472:
	s_add_i32 s8, s44, -15
	global_load_dwordx4 v[70:73], v[110:111], off
	global_load_dwordx4 v[74:77], v[134:135], off
	global_load_dwordx4 v[78:81], v[136:137], off
	global_load_dwordx4 v[66:69], v[138:139], off
	v_mov_b32_e32 v2, 0
	s_andn2_b64 vcc, exec, s[10:11]
	v_mov_b32_e32 v44, 0
	v_mov_b32_e32 v45, 0
	v_mov_b32_e32 v46, 0
	v_mov_b32_e32 v47, 0
	s_cbranch_vccnz .LBB0_474
	v_add_u32_e32 v3, s8, v195
	v_mad_i64_i32 v[4:5], s[10:11], v3, s30, v[132:133]
	v_add_u32_e32 v3, s8, v199
	v_mad_i64_i32 v[6:7], s[10:11], v3, s30, v[132:133]
	v_add_u32_e32 v3, s8, v200
	global_load_dwordx4 v[36:39], v[4:5], off
	global_load_dwordx4 v[40:43], v[6:7], off
	v_mad_i64_i32 v[4:5], s[10:11], v3, s30, v[132:133]
	global_load_dwordx4 v[44:47], v[4:5], off
	v_add_u32_e32 v3, v184, v198
	v_mov_b32_e32 v52, v3
.LBB0_474:
	v_add_u32_e32 v53, v184, v201
	s_or_b64 s[10:11], s[0:1], s[6:7]
	v_mov_b32_e32 v3, 0
	v_mov_b32_e32 v4, 0
	v_mov_b32_e32 v5, 0
	s_and_saveexec_b64 s[6:7], s[10:11]
	s_cbranch_execz .LBB0_476
	v_add_u32_e32 v2, s8, v202
	v_mad_i64_i32 v[2:3], s[10:11], v2, s30, v[132:133]
	global_load_dwordx4 v[2:5], v[2:3], off
.LBB0_476:
	s_or_b64 exec, exec, s[6:7]
	v_add_u32_e32 v6, s8, v204
	v_add_u32_e32 v8, s8, v205
	v_mad_i64_i32 v[6:7], s[6:7], v6, s30, v[132:133]
	v_mad_i64_i32 v[12:13], s[6:7], v8, s30, v[132:133]
	global_load_dwordx4 v[8:11], v[6:7], off
	s_nop 0
	global_load_dwordx4 v[12:15], v[12:13], off
	v_add_u32_e32 v6, s8, v206
	v_add_u32_e32 v16, s8, v207
	v_mad_i64_i32 v[6:7], s[6:7], v6, s30, v[132:133]
	v_mad_i64_i32 v[20:21], s[6:7], v16, s30, v[132:133]
	global_load_dwordx4 v[16:19], v[6:7], off
	s_nop 0
	global_load_dwordx4 v[20:23], v[20:21], off
	v_add_u32_e32 v6, s8, v208
	v_add_u32_e32 v24, s8, v209
	v_mad_i64_i32 v[6:7], s[6:7], v6, s30, v[132:133]
	v_mad_i64_i32 v[28:29], s[6:7], v24, s30, v[132:133]
	global_load_dwordx4 v[24:27], v[6:7], off
	s_nop 0
	global_load_dwordx4 v[28:31], v[28:29], off
	v_add_u32_e32 v6, s8, v210
	v_mad_i64_i32 v[6:7], s[6:7], v6, s30, v[132:133]
	global_load_dwordx4 v[32:35], v[6:7], off
	s_and_saveexec_b64 s[6:7], s[4:5]
	v_add_u32_e32 v48, s8, v211
	v_mad_i64_i32 v[48:49], s[10:11], v48, s30, v[132:133]
	global_load_dwordx4 v[48:51], v[48:49], off
	s_or_b64 exec, exec, s[6:7]
	v_add_u32_e32 v6, v184, v203
	s_waitcnt vmcnt(0)
	ds_write_b128 v53, v[44:47]
	s_cmp_eq_u32 s28, 0
	s_cbranch_scc1 .Lpsm_6
	ds_write_b128 v52, v[36:39]
	ds_write_b128 v52, v[40:43] offset:1088

.LBB0_478:
	s_or_b64 exec, exec, s[6:7]
	s_waitcnt lgkmcnt(0)
	s_ashr_i32 s8, s45, 6
	v_or_b32_e32 v2, s28, v1
	s_mul_i32 s10, s8, 15
	s_ashr_i32 s11, s10, 31
	v_add_u32_e32 v156, 0xfffff80f, v2
	v_cmp_eq_u32_e32 vcc, 0, v2
	v_cmp_lt_u32_e64 s[6:7], s36, v2
	v_lshl_add_u64 v[2:3], v[156:157], 0, s[10:11]
	v_lshlrev_b64 v[2:3], 11, v[2:3]
	v_lshl_add_u64 v[182:183], v[140:141], 0, v[2:3]
	v_mov_b32_e32 v2, 0
	s_mov_b32 s46, 0
	v_cndmask_b32_e64 v155, 0.5, 1.0, vcc
	s_mov_b64 s[10:11], 0
	v_mov_b32_e32 v3, v2
	v_mov_b32_e32 v4, v2
	v_mov_b32_e32 v5, v2
	v_mov_b32_e32 v6, v2
	v_mov_b32_e32 v7, v2
	v_mov_b32_e32 v8, v2
	v_mov_b32_e32 v9, v2
	v_mov_b32_e32 v10, v2
	v_mov_b32_e32 v11, v2
	v_mov_b32_e32 v12, v2
	v_mov_b32_e32 v13, v2
	v_mov_b32_e32 v14, v2
	v_mov_b32_e32 v15, v2
	v_mov_b32_e32 v16, v2
	v_mov_b32_e32 v17, v2
	v_mov_b32_e32 v18, v2
	v_mov_b32_e32 v19, v2
	v_mov_b32_e32 v20, v2
	v_mov_b32_e32 v21, v2
	v_mov_b32_e32 v22, v2
	v_mov_b32_e32 v23, v2
	v_mov_b32_e32 v24, v2
	v_mov_b32_e32 v25, v2
	v_mov_b32_e32 v26, v2
	v_mov_b32_e32 v27, v2
	v_mov_b32_e32 v28, v2
	v_mov_b32_e32 v29, v2
	v_mov_b32_e32 v30, v2
	v_mov_b32_e32 v31, v2
	v_mov_b32_e32 v32, v2
	v_mov_b32_e32 v33, v2
	v_mov_b32_e32 v34, v2
	v_mov_b32_e32 v35, v2
	v_mov_b32_e32 v36, v2
	v_mov_b32_e32 v37, v2
	v_mov_b32_e32 v38, v2
	v_mov_b32_e32 v39, v2
	v_mov_b32_e32 v40, v2
	v_mov_b32_e32 v41, v2
	v_mov_b32_e32 v42, v2
	v_mov_b32_e32 v43, v2
	v_mov_b32_e32 v44, v2
	v_mov_b32_e32 v45, v2
	v_mov_b32_e32 v46, v2
	v_mov_b32_e32 v47, v2
	v_mov_b32_e32 v48, v2
	v_mov_b32_e32 v49, v2
	v_mov_b32_e32 v50, v2
	v_mov_b32_e32 v51, v2
	v_mov_b32_e32 v52, v2
	v_mov_b32_e32 v53, v2
	v_mov_b32_e32 v54, v2
	v_mov_b32_e32 v55, v2
	v_mov_b32_e32 v56, v2
	v_mov_b32_e32 v57, v2
	v_mov_b32_e32 v58, v2
	v_mov_b32_e32 v59, v2
	v_mov_b32_e32 v60, v2
	v_mov_b32_e32 v61, v2
	v_mov_b32_e32 v62, v2
	v_mov_b32_e32 v63, v2
	v_mov_b32_e32 v64, v2
	s_waitcnt vmcnt(3)
	v_mov_b64_e32 v[84:85], v[72:73]
	s_waitcnt vmcnt(2)
	v_mov_b64_e32 v[88:89], v[76:77]
	s_waitcnt vmcnt(1)
	v_mov_b64_e32 v[92:93], v[80:81]
	s_waitcnt vmcnt(0)
	v_mov_b64_e32 v[96:97], v[68:69]
	v_mov_b32_e32 v65, v2
	v_mov_b64_e32 v[82:83], v[70:71]
	v_mov_b64_e32 v[86:87], v[74:75]
	v_mov_b64_e32 v[90:91], v[78:79]
	v_mov_b64_e32 v[94:95], v[66:67]
	s_cmpk_eq_i32 s10, 0xe0
	s_movk_i32 s8, 0x70
	s_cbranch_scc1 .LBB0_480

.LBB0_495:
	s_add_i32 s8, s44, -15
	global_load_dwordx4 v[70:73], v[122:123], off
	global_load_dwordx4 v[74:77], v[124:125], off
	global_load_dwordx4 v[78:81], v[126:127], off
	global_load_dwordx4 v[66:69], v[128:129], off
	v_mov_b32_e32 v2, 0
	s_andn2_b64 vcc, exec, s[6:7]
	v_mov_b32_e32 v44, 0
	v_mov_b32_e32 v45, 0
	v_mov_b32_e32 v46, 0
	v_mov_b32_e32 v47, 0
	s_cbranch_vccnz .LBB0_497
	v_add_u32_e32 v3, s8, v195
	v_mad_i64_i32 v[4:5], s[6:7], v3, s30, v[132:133]
	v_add_u32_e32 v3, s8, v199
	v_mad_i64_i32 v[6:7], s[6:7], v3, s30, v[132:133]
	v_add_u32_e32 v3, s8, v200
	global_load_dwordx4 v[36:39], v[4:5], off offset:256
	global_load_dwordx4 v[40:43], v[6:7], off offset:256
	v_mad_i64_i32 v[4:5], s[6:7], v3, s30, v[132:133]
	global_load_dwordx4 v[44:47], v[4:5], off offset:256
	v_add_u32_e32 v3, v184, v198
	v_mov_b32_e32 v52, v3
.LBB0_497:
	v_add_u32_e32 v53, v184, v201
	s_or_b64 s[6:7], s[0:1], s[2:3]
	v_mov_b32_e32 v3, 0
	v_mov_b32_e32 v4, 0
	v_mov_b32_e32 v5, 0
	s_and_saveexec_b64 s[2:3], s[6:7]
	s_cbranch_execz .LBB0_499
	v_add_u32_e32 v2, s8, v202
	v_mad_i64_i32 v[2:3], s[6:7], v2, s30, v[132:133]
	global_load_dwordx4 v[2:5], v[2:3], off offset:256
.LBB0_499:
	s_or_b64 exec, exec, s[2:3]
	v_add_u32_e32 v6, s8, v204
	v_add_u32_e32 v8, s8, v205
	v_mad_i64_i32 v[6:7], s[2:3], v6, s30, v[132:133]
	v_mad_i64_i32 v[12:13], s[2:3], v8, s30, v[132:133]
	global_load_dwordx4 v[8:11], v[6:7], off offset:256
	s_nop 0
	global_load_dwordx4 v[12:15], v[12:13], off offset:256
	v_add_u32_e32 v6, s8, v206
	v_add_u32_e32 v16, s8, v207
	v_mad_i64_i32 v[6:7], s[2:3], v6, s30, v[132:133]
	v_mad_i64_i32 v[20:21], s[2:3], v16, s30, v[132:133]
	global_load_dwordx4 v[16:19], v[6:7], off offset:256
	s_nop 0
	global_load_dwordx4 v[20:23], v[20:21], off offset:256
	v_add_u32_e32 v6, s8, v208
	v_add_u32_e32 v24, s8, v209
	v_mad_i64_i32 v[6:7], s[2:3], v6, s30, v[132:133]
	v_mad_i64_i32 v[28:29], s[2:3], v24, s30, v[132:133]
	global_load_dwordx4 v[24:27], v[6:7], off offset:256
	s_nop 0
	global_load_dwordx4 v[28:31], v[28:29], off offset:256
	v_add_u32_e32 v6, s8, v210
	v_mad_i64_i32 v[6:7], s[2:3], v6, s30, v[132:133]
	global_load_dwordx4 v[32:35], v[6:7], off offset:256
	s_and_saveexec_b64 s[2:3], s[4:5]
	v_add_u32_e32 v48, s8, v211
	v_mad_i64_i32 v[48:49], s[6:7], v48, s30, v[132:133]
	global_load_dwordx4 v[48:51], v[48:49], off offset:256
	s_or_b64 exec, exec, s[2:3]
	v_add_u32_e32 v6, v184, v203
	s_waitcnt vmcnt(0)
	ds_write_b128 v53, v[44:47]
	s_cmp_eq_u32 s28, 0
	s_cbranch_scc1 .Lpsm_7
	ds_write_b128 v52, v[36:39]
	ds_write_b128 v52, v[40:43] offset:1088

.LBB0_501:
	s_or_b64 exec, exec, s[2:3]
	s_waitcnt lgkmcnt(0)
	v_or_b32_e32 v2, s28, v1
	v_min_u32_e32 v3, 3, v2
	v_add_u32_e32 v3, 1, v3
	v_cvt_f32_ubyte0_e32 v3, v3
	v_div_scale_f32 v4, s[2:3], v3, v3, 1.0
	v_rcp_f32_e32 v5, v4
	s_ashr_i32 s2, s45, 6
	s_mul_i32 s2, s2, 15
	s_ashr_i32 s3, s2, 31
	v_fma_f32 v6, -v4, v5, 1.0
	v_fmac_f32_e32 v5, v6, v5
	v_div_scale_f32 v6, vcc, 1.0, v3, 1.0
	v_mul_f32_e32 v7, v6, v5
	v_fma_f32 v8, -v4, v7, v6
	v_fmac_f32_e32 v7, v8, v5
	v_fma_f32 v4, -v4, v7, v6
	v_div_fmas_f32 v4, v4, v5, v7
	v_add_u32_e32 v156, 0xfffff80f, v2
	v_div_fixup_f32 v155, v4, v3, 1.0
	v_cmp_lt_u32_e64 s[6:7], s36, v2
	v_lshl_add_u64 v[2:3], v[156:157], 0, s[2:3]
	v_lshlrev_b64 v[2:3], 11, v[2:3]
	v_lshl_add_u64 v[2:3], s[70:71], 0, v[2:3]
	v_mov_b32_e32 v161, v157
	v_lshl_add_u64 v[2:3], v[2:3], 0, v[160:161]
	v_lshl_add_u64 v[182:183], v[2:3], 0, s[26:27]
	v_mov_b32_e32 v2, 0
	s_mov_b32 s28, 0
	s_mov_b64 s[2:3], 0
	v_mov_b32_e32 v3, v2
	v_mov_b32_e32 v4, v2
	v_mov_b32_e32 v5, v2
	v_mov_b32_e32 v6, v2
	v_mov_b32_e32 v7, v2
	v_mov_b32_e32 v8, v2
	v_mov_b32_e32 v9, v2
	v_mov_b32_e32 v10, v2
	v_mov_b32_e32 v11, v2
	v_mov_b32_e32 v12, v2
	v_mov_b32_e32 v13, v2
	v_mov_b32_e32 v14, v2
	v_mov_b32_e32 v15, v2
	v_mov_b32_e32 v16, v2
	v_mov_b32_e32 v17, v2
	v_mov_b32_e32 v18, v2
	v_mov_b32_e32 v19, v2
	v_mov_b32_e32 v20, v2
	v_mov_b32_e32 v21, v2
	v_mov_b32_e32 v22, v2
	v_mov_b32_e32 v23, v2
	v_mov_b32_e32 v24, v2
	v_mov_b32_e32 v25, v2
	v_mov_b32_e32 v26, v2
	v_mov_b32_e32 v27, v2
	v_mov_b32_e32 v28, v2
	v_mov_b32_e32 v29, v2
	v_mov_b32_e32 v30, v2
	v_mov_b32_e32 v31, v2
	v_mov_b32_e32 v32, v2
	v_mov_b32_e32 v33, v2
	v_mov_b32_e32 v34, v2
	v_mov_b32_e32 v35, v2
	v_mov_b32_e32 v36, v2
	v_mov_b32_e32 v37, v2
	v_mov_b32_e32 v38, v2
	v_mov_b32_e32 v39, v2
	v_mov_b32_e32 v40, v2
	v_mov_b32_e32 v41, v2
	v_mov_b32_e32 v42, v2
	v_mov_b32_e32 v43, v2
	v_mov_b32_e32 v44, v2
	v_mov_b32_e32 v45, v2
	v_mov_b32_e32 v46, v2
	v_mov_b32_e32 v47, v2
	v_mov_b32_e32 v48, v2
	s_waitcnt vmcnt(3)
	v_mov_b64_e32 v[84:85], v[72:73]
	s_waitcnt vmcnt(2)
	v_mov_b64_e32 v[88:89], v[76:77]
	s_waitcnt vmcnt(1)
	v_mov_b64_e32 v[92:93], v[80:81]
	s_waitcnt vmcnt(0)
	v_mov_b64_e32 v[96:97], v[68:69]
	v_mov_b32_e32 v49, v2
	v_mov_b32_e32 v50, v2
	v_mov_b32_e32 v51, v2
	v_mov_b32_e32 v52, v2
	v_mov_b32_e32 v53, v2
	v_mov_b32_e32 v54, v2
	v_mov_b32_e32 v55, v2
	v_mov_b32_e32 v56, v2
	v_mov_b32_e32 v57, v2
	v_mov_b32_e32 v58, v2
	v_mov_b32_e32 v59, v2
	v_mov_b32_e32 v60, v2
	v_mov_b32_e32 v61, v2
	v_mov_b32_e32 v62, v2
	v_mov_b32_e32 v63, v2
	v_mov_b32_e32 v64, v2
	v_mov_b32_e32 v65, v2
	v_mov_b64_e32 v[82:83], v[70:71]
	v_mov_b64_e32 v[86:87], v[74:75]
	v_mov_b64_e32 v[90:91], v[78:79]
	v_mov_b64_e32 v[94:95], v[66:67]
	s_cmpk_eq_i32 s2, 0xe0
	s_movk_i32 s8, 0x70
	s_cbranch_scc1 .LBB0_503
